# NA bias softmax, second half-step block 1: all 16 bias LDS reads issued up front with recounted lgkmcnt waits instead of one read per element with a two-read lookahead
# baseline (speedup 1.0000x reference)
; template <int DQK, bool NA, bool SMAX, int LDV> ...
;     ...
;         if (NA && it >= 4) {
;           const int kr = rs + (it - 4);
;           const int ql = w * 32 + qt * 16 + fr, qr = r0 + (ql >> 6), qc = ql & 63;
;           const int rst = min(max(qr - 4, 0), 24);
;           const bool rowok = (kr >= rst) && (kr < rst + 8);
;           const int cst = min(max(qc - 8, 0), 48);
;           const int base = (kr - qr + 7) * 31 + 15 - qc;
;           float bv[4][4];
; #pragma unroll
;           for (int kt = 0; kt < 4; ++kt)
; #pragma unroll
;             for (int j = 0; j < 4; ++j) bv[kt][j] = rpbl[min(max(base + kt * 16 + fq * 4 + j, 0), 464)];
; #pragma unroll
;           for (int kt = 0; kt < 4; ++kt)
; #pragma unroll
;             for (int j = 0; j < 4; ++j) {
;               const int kc = kt * 16 + fq * 4 + j;
;               const float okf = (rowok && (kc >= cst) && (kc < cst + 16)) ? 1.f : 0.f;
;               const float pv = __builtin_amdgcn_exp2f(__builtin_fmaf(s[kt][qt][j], c1, bv[kt][j] - m0)) * okf;
;               s[kt][qt][j] = pv; sum += pv;
;             }
.LBB0_1085:
	s_movk_i32 s101, 0x100
	v_lshl_add_u32 v211, v208, 2, s101
	ds_read_b32 v0, v211 offset:41728
	ds_read_b32 v105, v211 offset:41732
	ds_read_b32 v3, v211 offset:41932
	ds_read_b32 v106, v211 offset:41736
	ds_read_b32 v107, v211 offset:41740
	ds_read_b32 v108, v211 offset:41792
	ds_read_b32 v109, v211 offset:41796
	ds_read_b32 v110, v211 offset:41800
	ds_read_b32 v111, v211 offset:41804
	ds_read_b32 v112, v211 offset:41856
	ds_read_b32 v113, v211 offset:41860
	ds_read_b32 v114, v211 offset:41864
	ds_read_b32 v115, v211 offset:41868
	ds_read_b32 v128, v211 offset:41920
	ds_read_b32 v129, v211 offset:41924
	ds_read_b32 v2, v211 offset:41928
	s_add_i32 s0, s19, s43
	s_add_i32 s0, s0, -3
	v_cmp_ge_i32_e32 vcc, s0, v164
	v_cmp_lt_i32_e64 s[0:1], s0, v163
	s_waitcnt lgkmcnt(15)
	s_or_b64 s[0:1], s[0:1], vcc
	v_fmac_f32_e32 v0, 0x3e38aa3b, v144
	s_waitcnt lgkmcnt(14)
	s_or_b64 s[26:27], s[0:1], s[58:59]
	v_exp_f32_e32 v0, v0
	v_fmac_f32_e32 v105, 0x3e38aa3b, v145
	v_cndmask_b32_e64 v104, v0, 0, s[26:27]
	v_readlane_b32 s26, v248, 21
	v_exp_f32_e32 v131, v105
	v_readlane_b32 s27, v248, 22
	s_or_b64 s[26:27], s[0:1], s[26:27]
	s_waitcnt lgkmcnt(12)
	v_mov_b32_e32 v0, v104
	v_cndmask_b32_e64 v105, v131, 0, s[26:27]
	v_fmac_f32_e32 v106, 0x3e38aa3b, v146
	v_add_f32_e32 v0, v0, v105
	v_exp_f32_e32 v131, v106
	s_or_b64 s[26:27], s[0:1], s[52:53]
	s_waitcnt lgkmcnt(11)
	v_cndmask_b32_e64 v106, v131, 0, s[26:27]
	v_fmac_f32_e32 v107, 0x3e38aa3b, v147
	v_add_f32_e32 v0, v0, v106
	v_exp_f32_e32 v131, v107
	s_or_b64 s[26:27], s[0:1], s[54:55]
	s_waitcnt lgkmcnt(10)
	v_cndmask_b32_e64 v107, v131, 0, s[26:27]
	v_fmac_f32_e32 v108, 0x3e38aa3b, v140
	v_add_f32_e32 v0, v0, v107
	v_exp_f32_e32 v131, v108
	s_or_b64 s[26:27], s[0:1], s[56:57]
	s_waitcnt lgkmcnt(9)
	v_cndmask_b32_e64 v130, v165, 0, s[26:27]
	v_fmac_f32_e32 v109, 0x3e38aa3b, v141
	v_mul_f32_e32 v108, v130, v131
	v_fmac_f32_e32 v0, v130, v131
	v_exp_f32_e32 v131, v109
	s_or_b64 s[26:27], s[0:1], s[60:61]
	s_waitcnt lgkmcnt(8)
	v_cndmask_b32_e64 v130, v166, 0, s[26:27]
	v_fmac_f32_e32 v110, 0x3e38aa3b, v142
	v_mul_f32_e32 v109, v130, v131
	v_fmac_f32_e32 v0, v130, v131
	v_exp_f32_e32 v131, v110
	s_or_b64 s[26:27], s[0:1], s[50:51]
	s_waitcnt lgkmcnt(7)
	v_cndmask_b32_e64 v130, v168, 0, s[26:27]
	v_fmac_f32_e32 v111, 0x3e38aa3b, v143
	v_mul_f32_e32 v110, v130, v131
	v_fmac_f32_e32 v0, v130, v131
	v_exp_f32_e32 v131, v111
	s_or_b64 s[26:27], s[0:1], s[64:65]
	s_waitcnt lgkmcnt(6)
	v_cndmask_b32_e64 v130, v169, 0, s[26:27]
	v_fmac_f32_e32 v112, 0x3e38aa3b, v136
	v_mul_f32_e32 v111, v130, v131
	v_fmac_f32_e32 v0, v130, v131
	v_exp_f32_e32 v131, v112
	s_or_b64 s[26:27], s[0:1], s[66:67]
	s_waitcnt lgkmcnt(5)
	v_cndmask_b32_e64 v130, v170, 0, s[26:27]
	v_fmac_f32_e32 v113, 0x3e38aa3b, v137
	v_mul_f32_e32 v112, v130, v131
	v_fmac_f32_e32 v0, v130, v131
	v_exp_f32_e32 v131, v113
	s_or_b64 s[26:27], s[0:1], s[68:69]
	s_waitcnt lgkmcnt(4)
	v_cndmask_b32_e64 v130, v171, 0, s[26:27]
	v_fmac_f32_e32 v114, 0x3e38aa3b, v138
	v_mul_f32_e32 v113, v130, v131
	v_fmac_f32_e32 v0, v130, v131
	v_exp_f32_e32 v131, v114
	s_or_b64 s[26:27], s[0:1], s[70:71]
	s_waitcnt lgkmcnt(3)
	v_cndmask_b32_e64 v130, v172, 0, s[26:27]
	v_fmac_f32_e32 v115, 0x3e38aa3b, v139
	v_mul_f32_e32 v114, v130, v131
	v_fmac_f32_e32 v0, v130, v131
	v_exp_f32_e32 v131, v115
	s_or_b64 s[26:27], s[0:1], s[72:73]
	s_waitcnt lgkmcnt(2)
	v_cndmask_b32_e64 v130, v173, 0, s[26:27]
	v_fmac_f32_e32 v128, 0x3e38aa3b, v132
	v_mul_f32_e32 v115, v130, v131
	v_fmac_f32_e32 v0, v130, v131
	v_exp_f32_e32 v131, v128
	s_waitcnt lgkmcnt(1)
	v_cndmask_b32_e64 v130, v174, 0, s[0:1]
	v_fmac_f32_e32 v129, 0x3e38aa3b, v133
	s_waitcnt lgkmcnt(0)
	v_mul_f32_e32 v128, v130, v131
	v_fmac_f32_e32 v0, v130, v131
	v_exp_f32_e32 v131, v129
	v_fmac_f32_e32 v2, 0x3e38aa3b, v134
	v_exp_f32_e32 v2, v2
	v_fmac_f32_e32 v3, 0x3e38aa3b, v135
	v_exp_f32_e32 v3, v3
	v_cndmask_b32_e64 v130, v175, 0, s[0:1]
	v_mul_f32_e32 v129, v130, v131
	v_fmac_f32_e32 v0, v130, v131
	v_cndmask_b32_e64 v131, v176, 0, s[0:1]
	v_mul_f32_e32 v130, v131, v2
	v_fmac_f32_e32 v0, v131, v2
	v_cndmask_b32_e64 v2, v177, 0, s[0:1]
	v_mul_f32_e32 v131, v2, v3
	v_fmac_f32_e32 v0, v2, v3
